# prologue S5 constants loop: the 32 Br/Bi loads of an index issued together and the per-step store-ack waits removed (was 16 serialized load+store round trips)
# baseline (speedup 1.0000x reference)
.LBB0_234:
	s_or_b64 exec, exec, s[0:1]
	s_waitcnt vmcnt(0)
	v_mul_f32_e32 v20, v17, v20
	v_mul_f32_e32 v23, 0x3fb8aa3b, v20
	v_fma_f32 v24, v20, s28, -v23
	v_rndne_f32_e32 v26, v23
	v_fmac_f32_e32 v24, 0x32a5705f, v20
	v_sub_f32_e32 v23, v23, v26
	v_add_f32_e32 v23, v23, v24
	v_exp_f32_e32 v23, v23
	v_cvt_i32_f32_e32 v24, v26
	v_cmp_ngt_f32_e32 vcc, s29, v20
	s_brev_b32 s0, 1
	v_lshrrev_b64 v[26:27], 11, v[8:9]
	v_ldexp_f32 v23, v23, v24
	v_cndmask_b32_e32 v23, 0, v23, vcc
	v_cmp_nlt_f32_e32 vcc, s33, v20
	v_mul_f32_e32 v20, v22, v22
	v_fmamk_f32 v24, v20, 0xb94c1982, v11
	v_fmaak_f32 v24, v20, v24, 0xbe2aaa9d
	v_mul_f32_e32 v24, v20, v24
	v_fmac_f32_e32 v22, v22, v24
	v_fmamk_f32 v24, v20, 0x37d75334, v12
	v_fmaak_f32 v24, v20, v24, 0x3d2aabf7
	v_fmaak_f32 v24, v20, v24, 0xbf000004
	v_fma_f32 v20, v20, v24, 1.0
	v_and_b32_e32 v24, 1, v21
	v_cndmask_b32_e32 v23, v10, v23, vcc
	v_cmp_eq_u32_e32 vcc, 0, v24
	v_lshlrev_b32_e32 v21, 30, v21
	v_and_b32_e32 v28, 0x7ff, v8
	v_cndmask_b32_e64 v20, -v22, v20, vcc
	v_bitop3_b32 v20, v21, v20, s0 bitop3:0x6c
	v_mul_f32_e32 v21, v25, v25
	v_fmamk_f32 v24, v21, 0xb94c1982, v11
	v_fmaak_f32 v24, v21, v24, 0xbe2aaa9d
	v_mul_f32_e32 v24, v21, v24
	v_fmac_f32_e32 v25, v25, v24
	v_fmamk_f32 v24, v21, 0x37d75334, v12
	v_fmaak_f32 v24, v21, v24, 0x3d2aabf7
	v_fmaak_f32 v24, v21, v24, 0xbf000004
	s_movk_i32 s0, 0x1f8
	v_fma_f32 v21, v21, v24, 1.0
	v_and_b32_e32 v24, 1, v4
	v_lshlrev_b32_e32 v4, 30, v4
	v_cmp_class_f32_e64 vcc, v18, s0
	v_cmp_eq_u32_e64 s[0:1], 0, v24
	v_and_b32_e32 v4, 0x80000000, v4
	v_xor_b32_e32 v18, v19, v18
	v_cndmask_b32_e64 v21, v21, v25, s[0:1]
	v_xor_b32_e32 v4, v18, v4
	v_xor_b32_e32 v4, v4, v21
	v_cndmask_b32_e32 v4, v15, v4, vcc
	v_lshlrev_b64 v[18:19], 14, v[26:27]
	v_cndmask_b32_e32 v22, v15, v20, vcc
	v_mul_f32_e32 v24, v23, v4
	v_lshl_add_u64 v[18:19], s[14:15], 0, v[18:19]
	v_lshlrev_b32_e32 v4, 2, v28
	v_mul_f32_e32 v20, v23, v22
	v_lshl_add_u64 v[18:19], v[18:19], 0, v[4:5]
	s_movk_i32 s0, 0x2000
	global_store_dword v[18:19], v20, off
	v_add_co_u32_e32 v18, vcc, s0, v18
	v_lshl_add_u64 v[20:21], s[26:27], 0, v[2:3]
	s_nop 0
	v_addc_co_u32_e32 v19, vcc, 0, v19, vcc
	global_store_dword v[18:19], v24, off
	v_lshl_add_u64 v[18:19], s[20:21], 0, v[2:3]
	global_load_dword v100, v[20:21], off
	global_load_dword v101, v[18:19], off
	global_load_dword v102, v[20:21], off offset:4
	global_load_dword v103, v[18:19], off offset:4
	global_load_dword v104, v[20:21], off offset:8
	global_load_dword v105, v[18:19], off offset:8
	global_load_dword v106, v[20:21], off offset:12
	global_load_dword v107, v[18:19], off offset:12
	global_load_dword v108, v[20:21], off offset:16
	global_load_dword v109, v[18:19], off offset:16
	global_load_dword v110, v[20:21], off offset:20
	global_load_dword v111, v[18:19], off offset:20
	global_load_dword v112, v[20:21], off offset:24
	global_load_dword v113, v[18:19], off offset:24
	global_load_dword v114, v[20:21], off offset:28
	global_load_dword v115, v[18:19], off offset:28
	global_load_dword v116, v[20:21], off offset:32
	global_load_dword v117, v[18:19], off offset:32
	global_load_dword v118, v[20:21], off offset:36
	global_load_dword v119, v[18:19], off offset:36
	global_load_dword v120, v[20:21], off offset:40
	global_load_dword v121, v[18:19], off offset:40
	global_load_dword v122, v[20:21], off offset:44
	global_load_dword v123, v[18:19], off offset:44
	global_load_dword v124, v[20:21], off offset:48
	global_load_dword v125, v[18:19], off offset:48
	global_load_dword v126, v[20:21], off offset:52
	global_load_dword v127, v[18:19], off offset:52
	global_load_dword v128, v[20:21], off offset:56
	global_load_dword v129, v[18:19], off offset:56
	global_load_dword v130, v[20:21], off offset:60
	global_load_dword v131, v[18:19], off offset:60
	s_waitcnt vmcnt(0)
	v_mov_b32_e32 v25, v100
	v_mov_b32_e32 v29, v101
	v_mul_f32_e32 v4, v16, v16
	v_fma_f32 v22, v23, v22, -1.0
	v_mul_f32_e32 v23, v16, v24
	v_fmac_f32_e32 v4, v17, v17
	v_fmac_f32_e32 v23, v17, v22
	v_div_scale_f32 v30, s[0:1], v4, v4, v23
	v_rcp_f32_e32 v31, v30
	v_mul_f32_e32 v16, v16, v22
	v_fma_f32 v16, v17, v24, -v16
	v_div_scale_f32 v17, s[0:1], v4, v4, v16
	v_fma_f32 v32, -v30, v31, 1.0
	v_fmac_f32_e32 v31, v32, v31
	v_div_scale_f32 v32, vcc, v23, v4, v23
	v_mul_f32_e32 v33, v32, v31
	v_fma_f32 v34, -v30, v33, v32
	v_rcp_f32_e32 v22, v17
	v_fmac_f32_e32 v33, v34, v31
	v_fma_f32 v30, -v30, v33, v32
	v_div_fmas_f32 v24, v30, v31, v33
	v_div_fixup_f32 v24, v24, v4, v23
	v_fma_f32 v23, -v17, v22, 1.0
	v_fmac_f32_e32 v22, v23, v22
	v_div_scale_f32 v23, vcc, v16, v4, v16
	v_mul_f32_e32 v30, v23, v22
	v_fma_f32 v31, -v17, v30, v23
	v_fmac_f32_e32 v30, v31, v22
	v_fma_f32 v17, -v17, v30, v23
	v_div_fmas_f32 v17, v17, v22, v30
	v_div_fixup_f32 v30, v17, v4, v16
	v_lshlrev_b64 v[16:17], 18, v[26:27]
	v_lshl_add_u64 v[16:17], s[16:17], 0, v[16:17]
	v_lshlrev_b32_e32 v4, 6, v28
	v_lshl_add_u64 v[16:17], v[16:17], 0, v[4:5]
	s_mov_b32 s0, 0x20000
	v_add_co_u32_e32 v22, vcc, s0, v16
	s_add_u32 s20, s20, s22
	s_nop 0
	v_addc_co_u32_e32 v23, vcc, 0, v17, vcc
	s_addc_u32 s21, s21, s23
	v_lshl_add_u64 v[8:9], v[8:9], 0, s[6:7]
	s_mov_b64 s[0:1], 0x1fff
	s_add_u32 s26, s26, s22
	v_cmp_lt_u64_e32 vcc, s[0:1], v[8:9]
	s_addc_u32 s27, s27, s23
	s_or_b64 s[30:31], vcc, s[30:31]
	v_lshl_add_u64 v[0:1], v[0:1], 0, s[18:19]
	v_mul_f32_e32 v4, v25, v30
	v_fma_f32 v4, v29, v24, -v4
	global_store_dword v[16:17], v4, off
	v_mul_f32_e32 v4, v25, v24
	v_fmac_f32_e32 v4, v29, v30
	global_store_dword v[22:23], v4, off
	v_mov_b32_e32 v4, v102
	s_nop 0
	v_mov_b32_e32 v25, v103
	v_mul_f32_e32 v26, v4, v30
	v_mul_f32_e32 v4, v4, v24
	v_fma_f32 v26, v25, v24, -v26
	v_fmac_f32_e32 v4, v25, v30
	global_store_dword v[16:17], v26, off offset:4
	global_store_dword v[22:23], v4, off offset:4
	v_mov_b32_e32 v4, v104
	s_nop 0
	v_mov_b32_e32 v25, v105
	v_mul_f32_e32 v26, v4, v30
	v_mul_f32_e32 v4, v4, v24
	v_fma_f32 v26, v25, v24, -v26
	v_fmac_f32_e32 v4, v25, v30
	global_store_dword v[16:17], v26, off offset:8
	global_store_dword v[22:23], v4, off offset:8
	v_mov_b32_e32 v4, v106
	s_nop 0
	v_mov_b32_e32 v25, v107
	v_mul_f32_e32 v26, v30, v4
	v_mul_f32_e32 v4, v24, v4
	v_fma_f32 v26, v24, v25, -v26
	v_fmac_f32_e32 v4, v30, v25
	global_store_dword v[16:17], v26, off offset:12
	global_store_dword v[22:23], v4, off offset:12
	v_mov_b32_e32 v4, v108
	s_nop 0
	v_mov_b32_e32 v25, v109
	v_mul_f32_e32 v26, v30, v4
	v_mul_f32_e32 v4, v24, v4
	v_fma_f32 v26, v24, v25, -v26
	v_fmac_f32_e32 v4, v30, v25
	global_store_dword v[16:17], v26, off offset:16
	global_store_dword v[22:23], v4, off offset:16
	v_mov_b32_e32 v4, v110
	s_nop 0
	v_mov_b32_e32 v25, v111
	v_mul_f32_e32 v26, v30, v4
	v_mul_f32_e32 v4, v24, v4
	v_fma_f32 v26, v24, v25, -v26
	v_fmac_f32_e32 v4, v30, v25
	global_store_dword v[16:17], v26, off offset:20
	global_store_dword v[22:23], v4, off offset:20
	v_mov_b32_e32 v4, v112
	s_nop 0
	v_mov_b32_e32 v25, v113
	v_mul_f32_e32 v26, v30, v4
	v_mul_f32_e32 v4, v24, v4
	v_fma_f32 v26, v24, v25, -v26
	v_fmac_f32_e32 v4, v30, v25
	global_store_dword v[16:17], v26, off offset:24
	global_store_dword v[22:23], v4, off offset:24
	v_mov_b32_e32 v4, v114
	s_nop 0
	v_mov_b32_e32 v25, v115
	v_mul_f32_e32 v26, v30, v4
	v_mul_f32_e32 v4, v24, v4
	v_fma_f32 v26, v24, v25, -v26
	v_fmac_f32_e32 v4, v30, v25
	global_store_dword v[16:17], v26, off offset:28
	global_store_dword v[22:23], v4, off offset:28
	v_mov_b32_e32 v4, v116
	s_nop 0
	v_mov_b32_e32 v25, v117
	v_mul_f32_e32 v26, v30, v4
	v_mul_f32_e32 v4, v24, v4
	v_fma_f32 v26, v24, v25, -v26
	v_fmac_f32_e32 v4, v30, v25
	global_store_dword v[16:17], v26, off offset:32
	global_store_dword v[22:23], v4, off offset:32
	v_mov_b32_e32 v4, v118
	s_nop 0
	v_mov_b32_e32 v25, v119
	v_mul_f32_e32 v26, v30, v4
	v_mul_f32_e32 v4, v24, v4
	v_fma_f32 v26, v24, v25, -v26
	v_fmac_f32_e32 v4, v30, v25
	global_store_dword v[16:17], v26, off offset:36
	global_store_dword v[22:23], v4, off offset:36
	v_mov_b32_e32 v4, v120
	s_nop 0
	v_mov_b32_e32 v25, v121
	v_mul_f32_e32 v26, v30, v4
	v_mul_f32_e32 v4, v24, v4
	v_fma_f32 v26, v24, v25, -v26
	v_fmac_f32_e32 v4, v30, v25
	global_store_dword v[16:17], v26, off offset:40
	global_store_dword v[22:23], v4, off offset:40
	v_mov_b32_e32 v4, v122
	s_nop 0
	v_mov_b32_e32 v25, v123
	v_mul_f32_e32 v26, v30, v4
	v_mul_f32_e32 v4, v24, v4
	v_fma_f32 v26, v24, v25, -v26
	v_fmac_f32_e32 v4, v30, v25
	global_store_dword v[16:17], v26, off offset:44
	global_store_dword v[22:23], v4, off offset:44
	v_mov_b32_e32 v4, v124
	s_nop 0
	v_mov_b32_e32 v25, v125
	v_mul_f32_e32 v26, v30, v4
	v_mul_f32_e32 v4, v24, v4
	v_fma_f32 v26, v24, v25, -v26
	v_fmac_f32_e32 v4, v30, v25
	global_store_dword v[16:17], v26, off offset:48
	global_store_dword v[22:23], v4, off offset:48
	v_mov_b32_e32 v4, v126
	s_nop 0
	v_mov_b32_e32 v25, v127
	v_mul_f32_e32 v26, v30, v4
	v_mul_f32_e32 v4, v24, v4
	v_fma_f32 v26, v24, v25, -v26
	v_fmac_f32_e32 v4, v30, v25
	global_store_dword v[16:17], v26, off offset:52
	global_store_dword v[22:23], v4, off offset:52
	v_mov_b32_e32 v4, v128
	s_nop 0
	v_mov_b32_e32 v25, v129
	v_mul_f32_e32 v26, v30, v4
	v_mul_f32_e32 v4, v24, v4
	v_fma_f32 v26, v24, v25, -v26
	v_fmac_f32_e32 v4, v30, v25
	global_store_dword v[16:17], v26, off offset:56
	global_store_dword v[22:23], v4, off offset:56
	v_mov_b32_e32 v4, v130
	s_nop 0
	v_mov_b32_e32 v18, v131
	v_mul_f32_e32 v19, v30, v4
	v_mul_f32_e32 v4, v24, v4
	v_fma_f32 v19, v24, v18, -v19
	v_fmac_f32_e32 v4, v30, v18
	global_store_dword v[16:17], v19, off offset:60
	global_store_dword v[22:23], v4, off offset:60
	s_andn2_b64 exec, exec, s[30:31]
	s_cbranch_execz .LBB0_243
